# attention k-loop: first score group's QK MFMAs issued first, second group's interleaved with the first group's max chain (no nop filler)
# speedup vs baseline: 1.0033x; 1.0033x over previous
; DEV f32x16 mfma32(bf16x8 a, bf16x8 b, f32x16 c) { return __builtin_amdgcn_mfma_f32_32x32x16_bf16(a, b, c, 0, 0, 0); }
; DEV void attn_item(const Params& p, int item, char* smem) {
;     ...
;     for (int jt = 0; jt < 2; jt++) {
; #pragma unroll
;       for (int r = 0; r < 16; r++) s[jt][r] = 0.f;
; #pragma unroll
;       for (int ks = 0; ks < 6; ks++) {
;         bf16x8 kf = *(const bf16x8*)(Kc + c31 * ASTR + ks * 16 + hf * 8);
;         s[jt] = mfma32(kf, qf[jt][ks], s[jt]);
;       }
;     }
; #pragma unroll
;     for (int jt = 0; jt < 2; jt++) {
;       float m0 = fmaxf(fmaxf(s[jt][0], s[jt][1]), fmaxf(s[jt][2], s[jt][3]));
;       float m1 = fmaxf(fmaxf(s[jt][4], s[jt][5]), fmaxf(s[jt][6], s[jt][7]));
;       float m2 = fmaxf(fmaxf(s[jt][8], s[jt][9]), fmaxf(s[jt][10], s[jt][11]));
;       float m3 = fmaxf(fmaxf(s[jt][12], s[jt][13]), fmaxf(s[jt][14], s[jt][15]));
;       const float mx = fmaxf(fmaxf(m0, m1), fmaxf(m2, m3));
;       if (__any(mx > mrun[jt])) {
;         const float mxa = fmaxf(mx, __shfl_xor(mx, 32));
;         const float mnew = fmaxf(mrun[jt], mxa);
;         const float alpha = __builtin_amdgcn_exp2f(mrun[jt] - mnew);
;         mrun[jt] = mnew;
;         lrun[jt] *= alpha;
; #pragma unroll
;         for (int dt = 0; dt < 2; dt++)
; #pragma unroll
;           for (int r = 0; r < 16; r++) o[dt][jt][r] *= alpha;
;       }
;       const float mcur = mrun[jt];
.LBB0_753:
	s_and_b32 s11, s12, 1
	s_mul_i32 s10, s11, 0x1a00
	v_add_u32_e32 v0, s10, v187
	ds_read_b128 v[2:5], v0
	ds_read_b128 v[6:9], v0 offset:32
	ds_read_b128 v[10:13], v0 offset:64
	ds_read_b128 v[240:243], v0 offset:96
	ds_read_b128 v[244:247], v0 offset:128
	ds_read_b128 v[236:239], v0 offset:160
	s_waitcnt lgkmcnt(5)
	v_mfma_f32_32x32x16_bf16 v[96:111], v[2:5], v[156:159], v[196:211]
	s_waitcnt lgkmcnt(4)
	v_mfma_f32_32x32x16_bf16 v[96:111], v[6:9], v[152:155], v[96:111]
	s_waitcnt lgkmcnt(3)
	v_mfma_f32_32x32x16_bf16 v[96:111], v[10:13], v[148:151], v[96:111]
	s_waitcnt lgkmcnt(2)
	v_mfma_f32_32x32x16_bf16 v[96:111], v[240:243], v[144:147], v[96:111]
	s_waitcnt lgkmcnt(1)
	v_mfma_f32_32x32x16_bf16 v[96:111], v[244:247], v[140:143], v[96:111]
	s_waitcnt lgkmcnt(0)
	v_mfma_f32_32x32x16_bf16 v[96:111], v[236:239], v[136:139], v[96:111]
	v_mfma_f32_32x32x16_bf16 v[80:95], v[2:5], v[132:135], v[220:235]
	v_mfma_f32_32x32x16_bf16 v[80:95], v[6:9], v[128:131], v[80:95]
	v_max3_f32 v0, v96, v97, v98
	v_max3_f32 v2, v99, v100, v101
	v_max3_f32 v3, v102, v103, v104
	v_max3_f32 v4, v105, v106, v107
	v_mfma_f32_32x32x16_bf16 v[80:95], v[10:13], v[112:115], v[80:95]
	v_max3_f32 v5, v108, v109, v110
	v_max3_f32 v0, v0, v2, v111
	v_max3_f32 v3, v3, v4, v5
	v_mfma_f32_32x32x16_bf16 v[80:95], v[240:243], v[116:119], v[80:95]
	v_max_f32_e32 v0, v0, v3
	v_cmp_gt_f32_e32 vcc, v0, v212
	v_mfma_f32_32x32x16_bf16 v[80:95], v[244:247], v[120:123], v[80:95]
	v_mfma_f32_32x32x16_bf16 v[80:95], v[236:239], v[124:127], v[80:95]
	s_cbranch_vccz .LBB0_755
	v_mbcnt_hi_u32_b32 v2, -1, v215
	v_and_b32_e32 v4, 64, v2
	v_xor_b32_e32 v3, 32, v2
	v_add_u32_e32 v4, 64, v4
	v_cmp_lt_i32_e32 vcc, v3, v4
	s_nop 1
	v_cndmask_b32_e32 v2, v2, v3, vcc
	v_lshlrev_b32_e32 v2, 2, v2
	ds_bpermute_b32 v2, v2, v0
	s_waitcnt lgkmcnt(0)
	v_max_f32_e32 v2, v0, v2
	v_exp_f32_e64 v0, -v2
	v_add_f32_e32 v185, v185, v2
	v_mov_b32_e32 v212, 0x41000000
	v_sub_f32_e32 v96, v96, v2
	v_sub_f32_e32 v97, v97, v2
	v_sub_f32_e32 v98, v98, v2
	v_sub_f32_e32 v99, v99, v2
	v_sub_f32_e32 v100, v100, v2
	v_sub_f32_e32 v101, v101, v2
	v_sub_f32_e32 v102, v102, v2
	v_sub_f32_e32 v103, v103, v2
	v_sub_f32_e32 v104, v104, v2
	v_sub_f32_e32 v105, v105, v2
	v_sub_f32_e32 v106, v106, v2
	v_sub_f32_e32 v107, v107, v2
	v_sub_f32_e32 v108, v108, v2
	v_sub_f32_e32 v109, v109, v2
	v_sub_f32_e32 v110, v110, v2
	v_sub_f32_e32 v111, v111, v2
	v_sub_f32_e32 v196, v196, v2
	v_sub_f32_e32 v197, v197, v2
	v_sub_f32_e32 v198, v198, v2
	v_sub_f32_e32 v199, v199, v2
	v_sub_f32_e32 v200, v200, v2
	v_sub_f32_e32 v201, v201, v2
	v_sub_f32_e32 v202, v202, v2
	v_sub_f32_e32 v203, v203, v2
	v_sub_f32_e32 v204, v204, v2
	v_sub_f32_e32 v205, v205, v2
	v_sub_f32_e32 v206, v206, v2
	v_sub_f32_e32 v207, v207, v2
	v_sub_f32_e32 v208, v208, v2
	v_sub_f32_e32 v209, v209, v2
	v_sub_f32_e32 v210, v210, v2
	v_sub_f32_e32 v211, v211, v2
	v_mul_f32_e32 v14, v14, v0
	v_pk_mul_f32 v[46:47], v[46:47], v[0:1] op_sel_hi:[1,0]
	v_pk_mul_f32 v[44:45], v[44:45], v[0:1] op_sel_hi:[1,0]
	v_pk_mul_f32 v[42:43], v[42:43], v[0:1] op_sel_hi:[1,0]
	v_pk_mul_f32 v[40:41], v[40:41], v[0:1] op_sel_hi:[1,0]
	v_pk_mul_f32 v[38:39], v[38:39], v[0:1] op_sel_hi:[1,0]
	v_pk_mul_f32 v[36:37], v[36:37], v[0:1] op_sel_hi:[1,0]
	v_pk_mul_f32 v[34:35], v[34:35], v[0:1] op_sel_hi:[1,0]
	v_pk_mul_f32 v[32:33], v[32:33], v[0:1] op_sel_hi:[1,0]
	v_pk_mul_f32 v[30:31], v[30:31], v[0:1] op_sel_hi:[1,0]
	v_pk_mul_f32 v[28:29], v[28:29], v[0:1] op_sel_hi:[1,0]
	v_pk_mul_f32 v[26:27], v[26:27], v[0:1] op_sel_hi:[1,0]
	v_pk_mul_f32 v[24:25], v[24:25], v[0:1] op_sel_hi:[1,0]
	v_pk_mul_f32 v[22:23], v[22:23], v[0:1] op_sel_hi:[1,0]
	v_pk_mul_f32 v[20:21], v[20:21], v[0:1] op_sel_hi:[1,0]
	v_pk_mul_f32 v[18:19], v[18:19], v[0:1] op_sel_hi:[1,0]
	v_pk_mul_f32 v[16:17], v[16:17], v[0:1] op_sel_hi:[1,0]
